# v31_stag3
# speedup vs baseline: 1.0446x; 1.0045x over previous
; __device__ __forceinline__ void attn_item(const bf16_t* __restrict__ Q, const bf16_t* __restrict__ Kp, const bf16_t* __restrict__ VT,
;                                           bf16_t* __restrict__ O, int ldo, int nvalid, const float* __restrict__ qn, const float* __restrict__ kn, bf16_t* sm) {
;     ...
;   const int lane = tid & 63, wave = tid >> 6, l15 = lane & 15, quad = lane >> 4;
;   const bool active = (wave * 32 < nvalid);
;   bf16x8 qf[2][4];
; #pragma unroll
;   for (int g = 0; g < 2; ++g)
; #pragma unroll
;     for (int ks = 0; ks < 4; ++ks) qf[g][ks] = *(const bf16x8*)(Q + (size_t)(wave * 32 + g * 16 + l15) * 128 + ks * 32 + quad * 8);
;   f32x4 o[2][8];
; #pragma unroll
;   for (int g = 0; g < 2; ++g)
; #pragma unroll
;     for (int dt = 0; dt < 8; ++dt) o[g][dt] = f32x4{0.f, 0.f, 0.f, 0.f};
;   float l[2] = {0.f, 0.f};
;   const float cscale = 0.08838834764831845f * 1.4426950408889634f;
;   float gq = fmaxf(fabsf(qn[lane]), fabsf(qn[lane + 64])), gk = fmaxf(fabsf(kn[lane]), fabsf(kn[lane + 64]));
; #pragma unroll
;   for (int sft = 32; sft > 0; sft >>= 1) { gq = fmaxf(gq, __shfl_xor(gq, sft)); gk = fmaxf(gk, __shfl_xor(gk, sft)); }
;   const float mc = 11.313708498984761f * gq * gk * 1.4426950408889634f;
;   u32x4 rkA[2], rvA[2], rkB[2], rvB[2];
;   const int krow = tid >> 4, kcc = (tid & 15) * 8;
;   const int vrow = tid >> 3, vcc = (tid & 7) * 8;
;   auto issue = [&](int tile, u32x4 (&rk)[2], u32x4 (&rv)[2]) {
; #pragma unroll
;     for (int i = 0; i < 2; ++i) {
;       rk[i] = *(const u32x4*)(Kp + (size_t)(tile * 64 + krow + 32 * i) * 128 + kcc);
;       rv[i] = *(const u32x4*)(VT + (size_t)(vrow + 64 * i) * LP + tile * 64 + vcc);
;     }
;   };
.LBB0_644:
	s_or_b64 exec, exec, s[6:7]
	v_lshrrev_b32_e32 v246, 6, v135
	s_nop 1
	v_readfirstlane_b32 s101, v246
	v_readlane_b32 s4, v255, 3
	v_mov_b32_e32 v72, v135
	v_readlane_b32 s5, v255, 4
	v_mov_b32_e32 v9, v1
	v_and_b32_e32 v8, 63, v72
	v_lshl_add_u64 v[4:5], v[4:5], 0, s[4:5]
	v_lshlrev_b32_e32 v8, 2, v8
	v_lshl_add_u64 v[6:7], v[6:7], 0, s[4:5]
	v_lshl_add_u64 v[4:5], v[4:5], 0, v[8:9]
	global_load_dword v34, v[4:5], off
	global_load_dword v35, v[4:5], off offset:256
	v_lshl_add_u64 v[4:5], v[6:7], 0, v[8:9]
	s_waitcnt lgkmcnt(0)
	global_load_dword v36, v[4:5], off offset:256
	global_load_dword v37, v[4:5], off
	v_cmp_lt_i32_e32 vcc, v159, v158
	v_sub_u32_e32 v73, 0x810, v0
	v_ashrrev_i32_e32 v24, 4, v72
	v_cndmask_b32_e32 v0, v157, v159, vcc
	v_cmp_lt_i32_e32 vcc, v160, v158
	v_ashrrev_i32_e32 v77, 3, v72
	v_ashrrev_i32_e32 v25, 31, v24
	v_cndmask_b32_e32 v4, v157, v160, vcc
	v_cmp_lt_i32_e32 vcc, v161, v158
	v_lshlrev_b32_e32 v168, 2, v4
	v_ashrrev_i32_e32 v4, 1, v72
	v_cndmask_b32_e32 v5, v157, v161, vcc
	v_cmp_lt_i32_e32 vcc, v162, v158
	v_lshlrev_b32_e32 v155, 2, v0
	v_lshlrev_b32_e32 v52, 2, v5
	v_cndmask_b32_e32 v6, v157, v162, vcc
	v_cmp_lt_i32_e32 vcc, v163, v158
	v_and_b32_e32 v0, 48, v72
	v_lshlrev_b32_e32 v5, 4, v72
	v_cndmask_b32_e32 v7, v157, v163, vcc
	v_and_b32_e32 v78, 0xffffffe0, v4
	v_add_u32_e32 v4, 64, v77
	v_lshlrev_b64 v[18:19], 8, v[24:25]
	v_mov_b32_e32 v21, v1
	v_mov_b32_e32 v23, v1
	v_lshlrev_b32_e32 v74, 2, v6
	v_lshlrev_b32_e32 v75, 2, v7
	v_lshl_add_u64 v[32:33], v[2:3], 0, v[0:1]
	v_and_b32_e32 v20, 0xf0, v5
	v_mad_i64_i32 v[2:3], s[4:5], v77, s66, v[16:17]
	v_and_b32_e32 v22, 0x70, v5
	v_mad_i64_i32 v[6:7], s[4:5], v4, s66, v[16:17]
	v_lshl_add_u64 v[8:9], v[14:15], 0, v[18:19]
	v_lshl_add_u64 v[28:29], v[2:3], 0, v[22:23]
	v_lshl_add_u64 v[26:27], v[6:7], 0, v[22:23]
	v_lshl_add_u64 v[30:31], v[8:9], 0, v[20:21]
	v_and_b32_e32 v76, 15, v72
	v_or_b32_e32 v142, v78, v76
	v_ashrrev_i32_e32 v143, 31, v142
	v_lshlrev_b64 v[10:11], 8, v[142:143]
	s_movk_i32 s4, 0x2000
	v_lshl_add_u64 v[42:43], v[32:33], 0, v[10:11]
	v_add_co_u32_e32 v44, vcc, s4, v30
	global_load_dwordx4 v[2:5], v[28:29], off
	global_load_dwordx4 v[6:9], v[26:27], off
	global_load_dwordx4 v[10:13], v[30:31], off
	v_addc_co_u32_e32 v45, vcc, 0, v31, vcc
	v_or_b32_e32 v140, 16, v142
	v_ashrrev_i32_e32 v141, 31, v140
	v_lshlrev_b64 v[50:51], 8, v[140:141]
	v_lshl_add_u64 v[32:33], v[32:33], 0, v[50:51]
	s_movk_i32 s4, 0x4000
	v_add_co_u32_e32 v70, vcc, s4, v30
	s_movk_i32 s4, 0x6000
	s_nop 0
	v_addc_co_u32_e32 v71, vcc, 0, v31, vcc
	s_movk_i32 s5, 0x110
	v_lshl_or_b32 v18, v76, 4, v18
	v_min_u32_e32 v169, 0x100, v73
	v_cmp_lt_i32_e64 s[6:7], v78, v169
	s_waitcnt vmcnt(6)
	v_max_f32_e64 v23, |v34|, |v34|
	s_waitcnt vmcnt(5)
	v_max_f32_e64 v21, |v35|, |v35|
	s_waitcnt vmcnt(4)
	v_max_f32_e64 v25, |v36|, |v36|
	s_waitcnt vmcnt(3)
	v_max_f32_e64 v34, |v37|, |v37|
	v_max_f32_e32 v21, v23, v21
	v_max_f32_e32 v23, v34, v25
	ds_bpermute_b32 v46, v155, v23
	ds_bpermute_b32 v25, v155, v21
	global_load_dwordx4 v[38:41], v[42:43], off
	global_load_dwordx4 v[34:37], v[42:43], off offset:64
	global_load_dwordx4 v[66:69], v[44:45], off
	s_waitcnt lgkmcnt(1)
	v_max_f32_e32 v44, v46, v46
	v_max_f32_e32 v23, v23, v44
	ds_bpermute_b32 v53, v168, v23
	s_waitcnt lgkmcnt(1)
	v_max_f32_e32 v25, v25, v25
	v_max_f32_e32 v21, v21, v25
	ds_bpermute_b32 v25, v168, v21
	global_load_dwordx4 v[46:49], v[42:43], off offset:128
	s_nop 0
	global_load_dwordx4 v[42:45], v[42:43], off offset:192
	s_waitcnt lgkmcnt(1)
	v_max_f32_e32 v50, v53, v53
	v_max_f32_e32 v23, v23, v50
	ds_bpermute_b32 v79, v52, v23
	s_waitcnt lgkmcnt(1)
	v_max_f32_e32 v25, v25, v25
	v_max_f32_e32 v21, v21, v25
	ds_bpermute_b32 v25, v52, v21
	global_load_dwordx4 v[62:65], v[32:33], off
	global_load_dwordx4 v[58:61], v[32:33], off offset:64
	global_load_dwordx4 v[54:57], v[32:33], off offset:128
	global_load_dwordx4 v[50:53], v[32:33], off offset:192
	s_waitcnt lgkmcnt(1)
	v_max_f32_e32 v32, v79, v79
	v_max_f32_e32 v23, v23, v32
	ds_bpermute_b32 v32, v74, v23
	s_waitcnt lgkmcnt(1)
	v_max_f32_e32 v25, v25, v25
	v_max_f32_e32 v21, v21, v25
	ds_bpermute_b32 v25, v74, v21
	s_waitcnt lgkmcnt(0)
	v_max_f32_e32 v74, v32, v32
	v_add_co_u32_e32 v32, vcc, s4, v30
	s_mov_b32 s4, 0x8000
	s_nop 0
	v_addc_co_u32_e32 v33, vcc, 0, v31, vcc
	s_barrier
; __device__ __forceinline__ void attn_item(const bf16_t* __restrict__ Q, const bf16_t* __restrict__ Kp, const bf16_t* __restrict__ VT,
;                                           bf16_t* __restrict__ O, int ldo, int nvalid, const float* __restrict__ qn, const float* __restrict__ kn, bf16_t* sm) {
;     ...
;   float gq = fmaxf(fabsf(qn[lane]), fabsf(qn[lane + 64])), gk = fmaxf(fabsf(kn[lane]), fabsf(kn[lane + 64]));
; #pragma unroll
;   for (int sft = 32; sft > 0; sft >>= 1) { gq = fmaxf(gq, __shfl_xor(gq, sft)); gk = fmaxf(gk, __shfl_xor(gk, sft)); }
;   const float mc = 11.313708498984761f * gq * gk * 1.4426950408889634f;
;   u32x4 rkA[2], rvA[2], rkB[2], rvB[2];
;   const int krow = tid >> 4, kcc = (tid & 15) * 8;
;   const int vrow = tid >> 3, vcc = (tid & 7) * 8;
;   auto issue = [&](int tile, u32x4 (&rk)[2], u32x4 (&rv)[2]) {
; #pragma unroll
;     for (int i = 0; i < 2; ++i) {
;       rk[i] = *(const u32x4*)(Kp + (size_t)(tile * 64 + krow + 32 * i) * 128 + kcc);
;       rv[i] = *(const u32x4*)(VT + (size_t)(vrow + 64 * i) * LP + tile * 64 + vcc);
;     }
;   };
;   auto stage = [&](u32x4 (&rk)[2], u32x4 (&rv)[2], int buf) {
; #pragma unroll
;     for (int i = 0; i < 2; ++i) {
;       *(u32x4*)(sK0 + buf * 64 * 136 + (krow + 32 * i) * 136 + kcc) = rk[i];
;       *(u32x4*)(sV0 + buf * 128 * 72 + (vrow + 64 * i) * 72 + vcc) = rv[i];
;     }
;   };
;     ...
;   issue(0, rkA, rvA);
;   __syncthreads();
;   stage(rkA, rvA, 0);
;   issue(1, rkA, rvA);
;   issue(2, rkB, rvB);
;   __syncthreads();
	global_load_dwordx4 v[98:101], v[70:71], off
	global_load_dwordx4 v[114:117], v[32:33], off
	v_add_co_u32_e32 v32, vcc, s4, v30
	s_mov_b32 s4, 0xa000
	s_nop 0
	v_addc_co_u32_e32 v33, vcc, 0, v31, vcc
	global_load_dwordx4 v[106:109], v[28:29], off offset:128
	global_load_dwordx4 v[110:113], v[28:29], off offset:256
	v_add_co_u32_e32 v28, vcc, s4, v30
	v_max_f32_e32 v25, v25, v25
	s_nop 0
	v_addc_co_u32_e32 v29, vcc, 0, v31, vcc
	global_load_dwordx4 v[102:105], v[32:33], off
	global_load_dwordx4 v[118:121], v[28:29], off
	global_load_dwordx4 v[126:129], v[26:27], off offset:128
	global_load_dwordx4 v[122:125], v[26:27], off offset:256
	v_max_f32_e32 v21, v21, v25
	ds_bpermute_b32 v25, v75, v21
	v_max_f32_e32 v23, v23, v74
	ds_bpermute_b32 v26, v75, v23
	v_cmp_lt_i32_e32 vcc, v164, v158
	v_bfe_u32 v28, v72, 4, 2
	s_waitcnt lgkmcnt(1)
	v_max_f32_e32 v25, v25, v25
	v_max_f32_e32 v21, v21, v25
	s_waitcnt lgkmcnt(0)
	v_max_f32_e32 v25, v26, v26
	v_cndmask_b32_e32 v26, v157, v164, vcc
	v_lshlrev_b32_e32 v26, 2, v26
	ds_bpermute_b32 v27, v26, v21
	v_max_f32_e32 v23, v23, v25
	ds_bpermute_b32 v25, v26, v23
	v_lshlrev_b32_e32 v29, 3, v28
	s_mov_b32 s4, 0
	s_waitcnt lgkmcnt(1)
	v_max_f32_e32 v26, v27, v27
	v_max_f32_e32 v21, v21, v26
	s_waitcnt lgkmcnt(0)
	v_max_f32_e32 v25, v25, v25
	v_max_f32_e32 v23, v23, v25
	v_mul_f32_e32 v21, 0x413504f3, v21
	v_mul_f32_e32 v21, v21, v23
	v_lshrrev_b32_e32 v231, 2, v24
	v_lshrrev_b32_e32 v232, 3, v24
	v_xor_b32_e32 v231, v231, v232
	v_and_b32_e32 v231, 1, v231
	v_lshlrev_b32_e32 v231, 4, v231
	v_xor_b32_e32 v230, v20, v231
	v_mad_u64_u32 v[146:147], s[8:9], v24, s5, v[230:231]
	s_movk_i32 s5, 0x90
	v_mad_u64_u32 v[148:149], s[8:9], v77, s5, v[22:23]
	s_waitcnt vmcnt(17)
	ds_write_b128 v146, v[10:13]
	ds_write_b128 v148, v[2:5] offset:34816
	s_waitcnt vmcnt(14)
	ds_write_b128 v146, v[66:69] offset:8704
	ds_write_b128 v148, v[6:9] offset:44032
	v_mul_u32_u24_e32 v2, 0x88, v76
	v_lshlrev_b32_e32 v2, 1, v2
	v_lshrrev_b32_e32 v233, 2, v76
	v_lshrrev_b32_e32 v234, 3, v76
	v_xor_b32_e32 v233, v233, v234
	v_and_b32_e32 v233, 1, v233
	v_lshlrev_b32_e32 v233, 4, v233
	v_xor_b32_e32 v0, v0, v233
	v_add_u32_e32 v171, v2, v0
	v_mul_u32_u24_e32 v0, 0x48, v76
	v_lshl_add_u32 v0, v0, 1, v29
	v_mad_i64_i32 v[26:27], s[8:9], v77, s66, 0
	v_lshlrev_b32_e32 v3, 7, v76
	v_add_u32_e32 v173, 0x10600, v0
	v_add_u32_e32 v174, 0x10f00, v0
	v_add_u32_e32 v176, 0x10640, v0
	v_add_u32_e32 v177, 0x10f40, v0
	v_and_b32_e32 v0, 7, v72
	v_sub_u32_e32 v2, v2, v3
	v_lshl_or_b32 v26, v0, 4, v26
	v_add_u32_e32 v149, v2, v29
	v_lshl_add_u64 v[2:3], v[16:17], 0, v[26:27]
	s_mov_b64 s[8:9], 0x42200
	v_lshl_add_u64 v[150:151], v[2:3], 0, s[8:9]
	v_lshl_add_u64 v[2:3], v[14:15], 0, v[18:19]
	s_mov_b64 s[8:9], 0x12000
	v_mov_b32_e32 v4, v1
	v_mov_b32_e32 v5, v1
	v_mul_f32_e32 v170, 0x3fb8aa3b, v21
	v_lshlrev_b32_e32 v147, 2, v28
	v_lshl_add_u64 v[152:153], v[2:3], 0, s[8:9]
	v_mov_b32_e32 v0, v1
	v_mov_b32_e32 v2, v1
	v_mov_b32_e32 v3, v1
	v_mov_b64_e32 v[8:9], v[4:5]
	v_mov_b64_e32 v[12:13], v[4:5]
	v_mov_b64_e32 v[16:17], v[4:5]
	v_mov_b64_e32 v[20:21], v[4:5]
	v_mov_b64_e32 v[24:25], v[4:5]
	v_mov_b64_e32 v[28:29], v[4:5]
	v_mov_b64_e32 v[32:33], v[4:5]
	v_mov_b64_e32 v[68:69], v[4:5]
	v_mov_b64_e32 v[72:73], v[4:5]
	v_mov_b64_e32 v[76:77], v[4:5]
	v_mov_b64_e32 v[80:81], v[4:5]
	v_mov_b64_e32 v[84:85], v[4:5]
	v_mov_b64_e32 v[88:89], v[4:5]
	v_mov_b64_e32 v[92:93], v[4:5]
	v_mov_b64_e32 v[96:97], v[4:5]
	v_add_u32_e32 v172, 0xd000, v149
	v_add_u32_e32 v175, 0xd040, v149
	v_mov_b64_e32 v[6:7], v[2:3]
	v_mov_b64_e32 v[10:11], v[2:3]
	v_mov_b64_e32 v[14:15], v[2:3]
	v_mov_b64_e32 v[18:19], v[2:3]
	v_mov_b64_e32 v[22:23], v[2:3]
	v_mov_b64_e32 v[26:27], v[2:3]
	v_mov_b64_e32 v[30:31], v[2:3]
	v_mov_b64_e32 v[66:67], v[2:3]
	v_mov_b64_e32 v[70:71], v[2:3]
	v_mov_b64_e32 v[74:75], v[2:3]
	v_mov_b64_e32 v[78:79], v[2:3]
	v_mov_b64_e32 v[82:83], v[2:3]
	v_mov_b64_e32 v[86:87], v[2:3]
	v_mov_b64_e32 v[90:91], v[2:3]
	v_mov_b64_e32 v[94:95], v[2:3]
	v_mov_b64_e32 v[144:145], v[0:1]
	s_waitcnt lgkmcnt(0)
	s_barrier
	s_branch .LBB0_646

; __device__ __forceinline__ f32x4 mfma16(bf16x8 a, bf16x8 b, f32x4 c) { return __builtin_amdgcn_mfma_f32_16x16x32_bf16(a, b, c, 0, 0, 0); }
; __device__ __forceinline__ void attn_item(const bf16_t* __restrict__ Q, const bf16_t* __restrict__ Kp, const bf16_t* __restrict__ VT,
;                                           bf16_t* __restrict__ O, int ldo, int nvalid, const float* __restrict__ qn, const float* __restrict__ kn, bf16_t* sm) {
;     ...
;     if (active) {
;       f32x4 s[2][4];
; #pragma unroll
;       for (int g = 0; g < 2; ++g)
; #pragma unroll
;         for (int kt = 0; kt < 4; ++kt) s[g][kt] = f32x4{0.f, 0.f, 0.f, 0.f};
;       {
;         bf16x8 kf[2][4];
; #pragma unroll
;         for (int ks = 0; ks < 4; ++ks) kf[0][ks] = *(const bf16x8*)(sK + (l15) * 136 + ks * 32 + quad * 8);
; #pragma unroll
;         for (int kt = 0; kt < 4; ++kt) {
;           if (kt + 1 < 4) {
; #pragma unroll
;             for (int ks = 0; ks < 4; ++ks) kf[(kt + 1) & 1][ks] = *(const bf16x8*)(sK + ((kt + 1) * 16 + l15) * 136 + ks * 32 + quad * 8);
;           }
;           SCHED();
; #pragma unroll
;           for (int ks = 0; ks < 4; ++ks) {
;             s[0][kt] = mfma16(kf[kt & 1][ks], qf[0][ks], s[0][kt]);
;             s[1][kt] = mfma16(kf[kt & 1][ks], qf[1][ks], s[1][kt]);
;           }
;           SCHED();
;         }
;       }
;       if (k0 + 64 > L) {
; #pragma unroll
;         for (int kt = 0; kt < 4; ++kt)
;           if (k0 + kt * 16 >= L) {
;             s[0][kt] = f32x4{-INFINITY, -INFINITY, -INFINITY, -INFINITY};
;             s[1][kt] = f32x4{-INFINITY, -INFINITY, -INFINITY, -INFINITY};
;           }
;       }
;       bf16x8 pf[2][2];
; #pragma unroll
;       for (int g = 0; g < 2; ++g) {
;         float rs = 0.f;
; #pragma unroll
;         for (int kt = 0; kt < 4; ++kt)
; #pragma unroll
;           for (int j = 0; j < 4; ++j) {
;             float pv = __builtin_amdgcn_exp2f(s[g][kt][j] * cscale - mc);
;             s[g][kt][j] = pv;
;             rs += pv;
;           }
;         l[g] += rs;
; #pragma unroll
;         for (int u = 0; u < 2; ++u) {
;           u32x4 w = {pack2(s[g][2 * u][0], s[g][2 * u][1]), pack2(s[g][2 * u][2], s[g][2 * u][3]),
;                      pack2(s[g][2 * u + 1][0], s[g][2 * u + 1][1]), pack2(s[g][2 * u + 1][2], s[g][2 * u + 1][3])};
;           pf[g][u] = *reinterpret_cast<bf16x8*>(&w);
;         }
;       }
.LBB0_648:
	s_and_saveexec_b64 s[8:9], s[6:7]
	s_cbranch_execz .LBB0_650
	s_cmp_lt_u32 s101, 4
	s_cbranch_scc1 .Lmy_nosleep_a
	s_sleep 3
.Lmy_nosleep_a:
	ds_read_b128 v[130:133], v171
	ds_read_b128 v[178:181], v171 offset:64
	ds_read_b128 v[182:185], v171 offset:128
	ds_read_b128 v[186:189], v171 offset:192
	ds_read_b128 v[190:193], v171 offset:4352
	ds_read_b128 v[194:197], v171 offset:4416
	ds_read_b128 v[198:201], v171 offset:4480
	ds_read_b128 v[202:205], v171 offset:4544
	s_waitcnt lgkmcnt(7)
	v_mfma_f32_16x16x32_bf16 v[206:209], v[130:133], v[38:41], 0
	v_mfma_f32_16x16x32_bf16 v[130:133], v[130:133], v[62:65], 0
	s_waitcnt lgkmcnt(6)
	v_mfma_f32_16x16x32_bf16 v[206:209], v[178:181], v[34:37], v[206:209]
	v_mfma_f32_16x16x32_bf16 v[130:133], v[178:181], v[58:61], v[130:133]
	s_waitcnt lgkmcnt(5)
	v_mfma_f32_16x16x32_bf16 v[178:181], v[182:185], v[46:49], v[206:209]
	v_mfma_f32_16x16x32_bf16 v[130:133], v[182:185], v[54:57], v[130:133]
	s_waitcnt lgkmcnt(4)
	v_mfma_f32_16x16x32_bf16 v[178:181], v[186:189], v[42:45], v[178:181]
	v_mfma_f32_16x16x32_bf16 v[182:185], v[186:189], v[50:53], v[130:133]
	s_nop 4
	ds_read_b128 v[130:133], v171 offset:8704
	ds_read_b128 v[186:189], v171 offset:8768
	ds_read_b128 v[206:209], v171 offset:8832
	ds_read_b128 v[210:213], v171 offset:8896
	s_waitcnt lgkmcnt(7)
	v_mfma_f32_16x16x32_bf16 v[214:217], v[190:193], v[38:41], 0
	v_mfma_f32_16x16x32_bf16 v[190:193], v[190:193], v[62:65], 0
	s_waitcnt lgkmcnt(6)
	v_mfma_f32_16x16x32_bf16 v[214:217], v[194:197], v[34:37], v[214:217]
	v_mfma_f32_16x16x32_bf16 v[190:193], v[194:197], v[58:61], v[190:193]
	s_waitcnt lgkmcnt(5)
	v_mfma_f32_16x16x32_bf16 v[194:197], v[198:201], v[46:49], v[214:217]
	v_mfma_f32_16x16x32_bf16 v[190:193], v[198:201], v[54:57], v[190:193]
	s_waitcnt lgkmcnt(4)
	v_mfma_f32_16x16x32_bf16 v[194:197], v[202:205], v[42:45], v[194:197]
	v_mfma_f32_16x16x32_bf16 v[190:193], v[202:205], v[50:53], v[190:193]
	ds_read_b128 v[198:201], v171 offset:13056
	ds_read_b128 v[202:205], v171 offset:13120
	ds_read_b128 v[214:217], v171 offset:13184
	ds_read_b128 v[218:221], v171 offset:13248
	s_waitcnt lgkmcnt(7)
	v_mfma_f32_16x16x32_bf16 v[222:225], v[130:133], v[38:41], 0
	v_mfma_f32_16x16x32_bf16 v[130:133], v[130:133], v[62:65], 0
	s_waitcnt lgkmcnt(6)
	v_mfma_f32_16x16x32_bf16 v[222:225], v[186:189], v[34:37], v[222:225]
	v_mfma_f32_16x16x32_bf16 v[130:133], v[186:189], v[58:61], v[130:133]
	s_waitcnt lgkmcnt(5)
	v_mfma_f32_16x16x32_bf16 v[186:189], v[206:209], v[46:49], v[222:225]
	v_mfma_f32_16x16x32_bf16 v[130:133], v[206:209], v[54:57], v[130:133]
	s_waitcnt lgkmcnt(4)
	v_mfma_f32_16x16x32_bf16 v[186:189], v[210:213], v[42:45], v[186:189]
	v_mfma_f32_16x16x32_bf16 v[206:209], v[210:213], v[50:53], v[130:133]
	s_waitcnt lgkmcnt(3)
	v_mfma_f32_16x16x32_bf16 v[130:133], v[198:201], v[38:41], 0
	v_mfma_f32_16x16x32_bf16 v[198:201], v[198:201], v[62:65], 0
	s_waitcnt lgkmcnt(2)
	v_mfma_f32_16x16x32_bf16 v[130:133], v[202:205], v[34:37], v[130:133]
	v_mfma_f32_16x16x32_bf16 v[198:201], v[202:205], v[58:61], v[198:201]
	s_waitcnt lgkmcnt(1)
	v_mfma_f32_16x16x32_bf16 v[130:133], v[214:217], v[46:49], v[130:133]
	v_mfma_f32_16x16x32_bf16 v[198:201], v[214:217], v[54:57], v[198:201]
	s_waitcnt lgkmcnt(0)
	v_mfma_f32_16x16x32_bf16 v[130:133], v[218:221], v[42:45], v[130:133]
	v_mfma_f32_16x16x32_bf16 v[198:201], v[218:221], v[50:53], v[198:201]
	v_add_u32_e32 v246, 0x8800, v149
	v_add_u32_e32 v247, 0x9000, v149
	v_add_u32_e32 v248, 0x9800, v149
	v_add_u32_e32 v249, 0xa000, v149
	ds_read2_b64 v[230:233], v246 offset1:4
	ds_read2_b64 v[234:237], v247 offset0:32 offset1:36
	ds_read2_b64 v[238:241], v248 offset0:64 offset1:68
	ds_read2_b64 v[242:245], v249 offset0:96 offset1:100
	v_fma_f32 v0, v178, s53, -v170
	v_exp_f32_e32 v202, v0
	v_fma_f32 v0, v179, s53, -v170
	v_exp_f32_e32 v204, v0
	v_fma_f32 v0, v180, s53, -v170
	v_exp_f32_e32 v210, v0
	v_fma_f32 v0, v181, s53, -v170
	v_exp_f32_e32 v212, v0
	v_fma_f32 v0, v194, s53, -v170
	v_exp_f32_e32 v194, v0
	v_fma_f32 v0, v195, s53, -v170
	v_exp_f32_e32 v214, v0
	v_fma_f32 v0, v196, s53, -v170
	v_exp_f32_e32 v196, v0
	v_fma_f32 v0, v197, s53, -v170
	v_exp_f32_e32 v216, v0
	v_fma_f32 v0, v186, s53, -v170
	v_exp_f32_e32 v186, v0
	v_fma_f32 v0, v187, s53, -v170
	v_exp_f32_e32 v218, v0
	v_fma_f32 v0, v188, s53, -v170
	v_exp_f32_e32 v188, v0
	v_fma_f32 v0, v189, s53, -v170
	v_exp_f32_e32 v220, v0
	v_fma_f32 v0, v130, s53, -v170
	v_exp_f32_e32 v222, v0
	v_fma_f32 v0, v131, s53, -v170
	v_exp_f32_e32 v224, v0
	v_fma_f32 v0, v132, s53, -v170
	v_exp_f32_e32 v226, v0
	v_fma_f32 v0, v133, s53, -v170
	v_exp_f32_e32 v228, v0
	v_fma_f32 v0, v182, s53, -v170
	v_exp_f32_e32 v203, v0
	v_fma_f32 v0, v183, s53, -v170
	v_exp_f32_e32 v205, v0
	v_fma_f32 v0, v184, s53, -v170
	v_exp_f32_e32 v211, v0
	v_fma_f32 v0, v185, s53, -v170
	v_exp_f32_e32 v213, v0
	v_fma_f32 v0, v190, s53, -v170
	v_exp_f32_e32 v195, v0
	v_fma_f32 v0, v191, s53, -v170
	v_pk_add_f32 v[182:183], v[202:203], 0 op_sel_hi:[1,0]
	v_exp_f32_e32 v215, v0
	v_fma_f32 v0, v192, s53, -v170
	v_pk_add_f32 v[182:183], v[204:205], v[182:183]
	v_exp_f32_e32 v197, v0
	v_fma_f32 v0, v193, s53, -v170
	v_pk_add_f32 v[182:183], v[210:211], v[182:183]
; __device__ __forceinline__ f32x4 mfma16(bf16x8 a, bf16x8 b, f32x4 c) { return __builtin_amdgcn_mfma_f32_16x16x32_bf16(a, b, c, 0, 0, 0); }
; #define SCHED() __builtin_amdgcn_sched_barrier(0)
; __device__ __forceinline__ void attn_item(const bf16_t* __restrict__ Q, const bf16_t* __restrict__ Kp, const bf16_t* __restrict__ VT,
;                                           bf16_t* __restrict__ O, int ldo, int nvalid, const float* __restrict__ qn, const float* __restrict__ kn, bf16_t* sm) {
;     ...
;       bf16x8 pf[2][2];
; #pragma unroll
;       for (int g = 0; g < 2; ++g) {
;         float rs = 0.f;
; #pragma unroll
;         for (int kt = 0; kt < 4; ++kt)
; #pragma unroll
;           for (int j = 0; j < 4; ++j) {
;             float pv = __builtin_amdgcn_exp2f(s[g][kt][j] * cscale - mc);
;             s[g][kt][j] = pv;
;             rs += pv;
;           }
;         l[g] += rs;
; #pragma unroll
;         for (int u = 0; u < 2; ++u) {
;           u32x4 w = {pack2(s[g][2 * u][0], s[g][2 * u][1]), pack2(s[g][2 * u][2], s[g][2 * u][3]),
;                      pack2(s[g][2 * u + 1][0], s[g][2 * u + 1][1]), pack2(s[g][2 * u + 1][2], s[g][2 * u + 1][3])};
;           pf[g][u] = *reinterpret_cast<bf16x8*>(&w);
;         }
;       }
; #pragma unroll
;       for (int u = 0; u < 2; ++u) {
;         bf16x8 vf[8];
; #pragma unroll
;         for (int dt = 0; dt < 8; ++dt) {
;           u32x2 v0 = *(const u32x2*)(sV + (dt * 16 + l15) * 72 + (2 * u) * 16 + quad * 4);
;           u32x2 v1 = *(const u32x2*)(sV + (dt * 16 + l15) * 72 + (2 * u + 1) * 16 + quad * 4);
;           u32x4 w = {v0.x, v0.y, v1.x, v1.y};
;           vf[dt] = *reinterpret_cast<bf16x8*>(&w);
;         }
;         SCHED();
; #pragma unroll
;         for (int dt = 0; dt < 8; ++dt) {
;           o[0][dt] = mfma16(vf[dt], pf[0][u], o[0][dt]);
;           o[1][dt] = mfma16(vf[dt], pf[1][u], o[1][dt]);
;         }
;         SCHED();
;       }
	v_exp_f32_e32 v217, v0
	v_fma_f32 v0, v206, s53, -v170
	v_pk_add_f32 v[182:183], v[212:213], v[182:183]
	v_exp_f32_e32 v187, v0
	v_fma_f32 v0, v207, s53, -v170
	v_pk_add_f32 v[182:183], v[182:183], v[194:195]
	v_exp_f32_e32 v219, v0
	v_pk_add_f32 v[182:183], v[214:215], v[182:183]
	v_fma_f32 v0, v208, s53, -v170
	v_pk_add_f32 v[182:183], v[196:197], v[182:183]
	v_exp_f32_e32 v189, v0
	v_fma_f32 v0, v209, s53, -v170
	v_pk_add_f32 v[182:183], v[216:217], v[182:183]
	v_exp_f32_e32 v221, v0
	v_fma_f32 v0, v198, s53, -v170
	v_pk_add_f32 v[182:183], v[182:183], v[186:187]
	v_exp_f32_e32 v223, v0
	v_fma_f32 v0, v199, s53, -v170
	v_pk_add_f32 v[182:183], v[218:219], v[182:183]
	v_exp_f32_e32 v225, v0
	v_fma_f32 v0, v200, s53, -v170
	v_exp_f32_e32 v227, v0
	v_fma_f32 v0, v201, s53, -v170
	v_pk_add_f32 v[182:183], v[188:189], v[182:183]
	v_exp_f32_e32 v229, v0
	v_pk_add_f32 v[182:183], v[220:221], v[182:183]
	v_cvt_pk_bf16_f32 v178, v202, v204
	v_cvt_pk_bf16_f32 v179, v210, v212
	v_cvt_pk_bf16_f32 v180, v194, v214
	v_cvt_pk_bf16_f32 v181, v196, v216
	v_cvt_pk_bf16_f32 v130, v186, v218
	s_nop 0
	v_pk_add_f32 v[182:183], v[182:183], v[222:223]
	v_cvt_pk_bf16_f32 v131, v188, v220
	v_cvt_pk_bf16_f32 v132, v222, v224
	v_cvt_pk_bf16_f32 v133, v226, v228
	v_add_u32_e32 v0, 0x8800, v149
	v_pk_add_f32 v[182:183], v[224:225], v[182:183]
	v_add_u32_e32 v222, 0x9000, v149
	v_pk_add_f32 v[182:183], v[226:227], v[182:183]
	v_add_u32_e32 v224, 0xa000, v149
	v_pk_add_f32 v[182:183], v[228:229], v[182:183]
	v_add_u32_e32 v226, 0xb000, v149
	v_pk_add_f32 v[144:145], v[144:145], v[182:183]
	v_cvt_pk_bf16_f32 v182, v203, v205
	v_cvt_pk_bf16_f32 v183, v211, v213
	v_cvt_pk_bf16_f32 v184, v195, v215
	v_cvt_pk_bf16_f32 v185, v197, v217
	v_cvt_pk_bf16_f32 v186, v187, v219
	v_cvt_pk_bf16_f32 v187, v189, v221
	v_cvt_pk_bf16_f32 v188, v223, v225
	v_cvt_pk_bf16_f32 v189, v227, v229
	v_add_u32_e32 v223, 0x9800, v149
	v_add_u32_e32 v225, 0xa800, v149
	v_add_u32_e32 v227, 0xb800, v149
	v_add_u32_e32 v228, 0xc000, v149
	ds_read2_b64 v[206:209], v225 offset0:128 offset1:132
	ds_read2_b64 v[210:213], v226 offset0:160 offset1:164
	ds_read2_b64 v[214:217], v227 offset0:192 offset1:196
	ds_read2_b64 v[218:221], v228 offset0:224 offset1:228
	s_waitcnt lgkmcnt(7)
	v_mfma_f32_16x16x32_bf16 v[94:97], v[230:233], v[178:181], v[94:97]
	v_mfma_f32_16x16x32_bf16 v[30:33], v[230:233], v[182:185], v[30:33]
	s_waitcnt lgkmcnt(6)
	v_mfma_f32_16x16x32_bf16 v[90:93], v[234:237], v[178:181], v[90:93]
	v_mfma_f32_16x16x32_bf16 v[26:29], v[234:237], v[182:185], v[26:29]
	s_waitcnt lgkmcnt(5)
	v_mfma_f32_16x16x32_bf16 v[86:89], v[238:241], v[178:181], v[86:89]
	v_mfma_f32_16x16x32_bf16 v[22:25], v[238:241], v[182:185], v[22:25]
	s_waitcnt lgkmcnt(4)
	v_mfma_f32_16x16x32_bf16 v[82:85], v[242:245], v[178:181], v[82:85]
	v_mfma_f32_16x16x32_bf16 v[18:21], v[242:245], v[182:185], v[18:21]
	s_waitcnt lgkmcnt(3)
	v_mfma_f32_16x16x32_bf16 v[78:81], v[206:209], v[178:181], v[78:81]
	v_mfma_f32_16x16x32_bf16 v[14:17], v[206:209], v[182:185], v[14:17]
	s_waitcnt lgkmcnt(2)
	v_mfma_f32_16x16x32_bf16 v[74:77], v[210:213], v[178:181], v[74:77]
	v_mfma_f32_16x16x32_bf16 v[10:13], v[210:213], v[182:185], v[10:13]
	s_waitcnt lgkmcnt(1)
	v_mfma_f32_16x16x32_bf16 v[70:73], v[214:217], v[178:181], v[70:73]
	v_mfma_f32_16x16x32_bf16 v[6:9], v[214:217], v[182:185], v[6:9]
	s_waitcnt lgkmcnt(0)
	v_mfma_f32_16x16x32_bf16 v[66:69], v[218:221], v[178:181], v[66:69]
	v_mfma_f32_16x16x32_bf16 v[2:5], v[218:221], v[182:185], v[2:5]
	ds_read2_b64 v[178:181], v0 offset0:8 offset1:12
	ds_read2_b64 v[182:185], v222 offset0:40 offset1:44
	ds_read2_b64 v[190:193], v223 offset0:72 offset1:76
	ds_read2_b64 v[194:197], v224 offset0:104 offset1:108
	ds_read2_b64 v[198:201], v225 offset0:136 offset1:140
	ds_read2_b64 v[202:205], v226 offset0:168 offset1:172
	ds_read2_b64 v[206:209], v227 offset0:200 offset1:204
	ds_read2_b64 v[210:213], v228 offset0:232 offset1:236
	s_waitcnt lgkmcnt(7)
	v_mfma_f32_16x16x32_bf16 v[94:97], v[178:181], v[130:133], v[94:97]
	v_mfma_f32_16x16x32_bf16 v[30:33], v[178:181], v[186:189], v[30:33]
	s_waitcnt lgkmcnt(6)
	v_mfma_f32_16x16x32_bf16 v[90:93], v[182:185], v[130:133], v[90:93]
	v_mfma_f32_16x16x32_bf16 v[26:29], v[182:185], v[186:189], v[26:29]
	s_waitcnt lgkmcnt(5)
	v_mfma_f32_16x16x32_bf16 v[86:89], v[190:193], v[130:133], v[86:89]
	v_mfma_f32_16x16x32_bf16 v[22:25], v[190:193], v[186:189], v[22:25]
	s_waitcnt lgkmcnt(4)
	v_mfma_f32_16x16x32_bf16 v[82:85], v[194:197], v[130:133], v[82:85]
	v_mfma_f32_16x16x32_bf16 v[18:21], v[194:197], v[186:189], v[18:21]
	s_waitcnt lgkmcnt(3)
	v_mfma_f32_16x16x32_bf16 v[78:81], v[198:201], v[130:133], v[78:81]
	v_mfma_f32_16x16x32_bf16 v[14:17], v[198:201], v[186:189], v[14:17]
	s_waitcnt lgkmcnt(2)
	v_mfma_f32_16x16x32_bf16 v[74:77], v[202:205], v[130:133], v[74:77]
	v_mfma_f32_16x16x32_bf16 v[10:13], v[202:205], v[186:189], v[10:13]
	s_waitcnt lgkmcnt(1)
	v_mfma_f32_16x16x32_bf16 v[70:73], v[206:209], v[130:133], v[70:73]
	v_mfma_f32_16x16x32_bf16 v[6:9], v[206:209], v[186:189], v[6:9]
	s_waitcnt lgkmcnt(0)
	v_mfma_f32_16x16x32_bf16 v[66:69], v[210:213], v[130:133], v[66:69]
	v_mfma_f32_16x16x32_bf16 v[2:5], v[210:213], v[186:189], v[2:5]

; __device__ __forceinline__ f32x4 mfma16(bf16x8 a, bf16x8 b, f32x4 c) { return __builtin_amdgcn_mfma_f32_16x16x32_bf16(a, b, c, 0, 0, 0); }
; __device__ __forceinline__ void attn_item(const bf16_t* __restrict__ Q, const bf16_t* __restrict__ Kp, const bf16_t* __restrict__ VT,
;                                           bf16_t* __restrict__ O, int ldo, int nvalid, const float* __restrict__ qn, const float* __restrict__ kn, bf16_t* sm) {
;     ...
;     if (active) {
;       f32x4 s[2][4];
; #pragma unroll
;       for (int g = 0; g < 2; ++g)
; #pragma unroll
;         for (int kt = 0; kt < 4; ++kt) s[g][kt] = f32x4{0.f, 0.f, 0.f, 0.f};
;       {
;         bf16x8 kf[2][4];
; #pragma unroll
;         for (int ks = 0; ks < 4; ++ks) kf[0][ks] = *(const bf16x8*)(sK + (l15) * 136 + ks * 32 + quad * 8);
; #pragma unroll
;         for (int kt = 0; kt < 4; ++kt) {
;           if (kt + 1 < 4) {
; #pragma unroll
;             for (int ks = 0; ks < 4; ++ks) kf[(kt + 1) & 1][ks] = *(const bf16x8*)(sK + ((kt + 1) * 16 + l15) * 136 + ks * 32 + quad * 8);
;           }
;           SCHED();
; #pragma unroll
;           for (int ks = 0; ks < 4; ++ks) {
;             s[0][kt] = mfma16(kf[kt & 1][ks], qf[0][ks], s[0][kt]);
;             s[1][kt] = mfma16(kf[kt & 1][ks], qf[1][ks], s[1][kt]);
;           }
;           SCHED();
;         }
;       }
;       if (k0 + 64 > L) {
; #pragma unroll
;         for (int kt = 0; kt < 4; ++kt)
;           if (k0 + kt * 16 >= L) {
;             s[0][kt] = f32x4{-INFINITY, -INFINITY, -INFINITY, -INFINITY};
;             s[1][kt] = f32x4{-INFINITY, -INFINITY, -INFINITY, -INFINITY};
;           }
;       }
;       bf16x8 pf[2][2];
; #pragma unroll
;       for (int g = 0; g < 2; ++g) {
;         float rs = 0.f;
; #pragma unroll
;         for (int kt = 0; kt < 4; ++kt)
; #pragma unroll
;           for (int j = 0; j < 4; ++j) {
;             float pv = __builtin_amdgcn_exp2f(s[g][kt][j] * cscale - mc);
;             s[g][kt][j] = pv;
;             rs += pv;
;           }
;         l[g] += rs;
; #pragma unroll
;         for (int u = 0; u < 2; ++u) {
;           u32x4 w = {pack2(s[g][2 * u][0], s[g][2 * u][1]), pack2(s[g][2 * u][2], s[g][2 * u][3]),
;                      pack2(s[g][2 * u + 1][0], s[g][2 * u + 1][1]), pack2(s[g][2 * u + 1][2], s[g][2 * u + 1][3])};
;           pf[g][u] = *reinterpret_cast<bf16x8*>(&w);
;         }
;       }
.Lmy_nosleep_b:
	ds_read_b128 v[130:133], v171 offset:17408
	ds_read_b128 v[178:181], v171 offset:17472
	ds_read_b128 v[182:185], v171 offset:17536
	ds_read_b128 v[186:189], v171 offset:17600
	ds_read_b128 v[190:193], v171 offset:21760
	ds_read_b128 v[194:197], v171 offset:21824
	ds_read_b128 v[198:201], v171 offset:21888
	ds_read_b128 v[202:205], v171 offset:21952
	s_waitcnt lgkmcnt(7)
	v_mfma_f32_16x16x32_bf16 v[206:209], v[130:133], v[38:41], 0
	v_mfma_f32_16x16x32_bf16 v[130:133], v[130:133], v[62:65], 0
	s_waitcnt lgkmcnt(6)
	v_mfma_f32_16x16x32_bf16 v[206:209], v[178:181], v[34:37], v[206:209]
	v_mfma_f32_16x16x32_bf16 v[130:133], v[178:181], v[58:61], v[130:133]
	s_waitcnt lgkmcnt(5)
	v_mfma_f32_16x16x32_bf16 v[178:181], v[182:185], v[46:49], v[206:209]
	v_mfma_f32_16x16x32_bf16 v[130:133], v[182:185], v[54:57], v[130:133]
	s_waitcnt lgkmcnt(4)
	v_mfma_f32_16x16x32_bf16 v[178:181], v[186:189], v[42:45], v[178:181]
	v_mfma_f32_16x16x32_bf16 v[182:185], v[186:189], v[50:53], v[130:133]
	s_nop 4
	ds_read_b128 v[130:133], v171 offset:26112
	ds_read_b128 v[186:189], v171 offset:26176
	ds_read_b128 v[206:209], v171 offset:26240
	ds_read_b128 v[210:213], v171 offset:26304
	s_waitcnt lgkmcnt(7)
	v_mfma_f32_16x16x32_bf16 v[214:217], v[190:193], v[38:41], 0
	v_mfma_f32_16x16x32_bf16 v[190:193], v[190:193], v[62:65], 0
	s_waitcnt lgkmcnt(6)
	v_mfma_f32_16x16x32_bf16 v[214:217], v[194:197], v[34:37], v[214:217]
	v_mfma_f32_16x16x32_bf16 v[190:193], v[194:197], v[58:61], v[190:193]
	s_waitcnt lgkmcnt(5)
	v_mfma_f32_16x16x32_bf16 v[194:197], v[198:201], v[46:49], v[214:217]
	v_mfma_f32_16x16x32_bf16 v[190:193], v[198:201], v[54:57], v[190:193]
	s_waitcnt lgkmcnt(4)
	v_mfma_f32_16x16x32_bf16 v[194:197], v[202:205], v[42:45], v[194:197]
	v_mfma_f32_16x16x32_bf16 v[190:193], v[202:205], v[50:53], v[190:193]
	ds_read_b128 v[198:201], v171 offset:30464
	ds_read_b128 v[202:205], v171 offset:30528
	ds_read_b128 v[214:217], v171 offset:30592
	ds_read_b128 v[218:221], v171 offset:30656
	s_waitcnt lgkmcnt(7)
	v_mfma_f32_16x16x32_bf16 v[222:225], v[130:133], v[38:41], 0
	v_mfma_f32_16x16x32_bf16 v[130:133], v[130:133], v[62:65], 0
	s_waitcnt lgkmcnt(6)
	v_mfma_f32_16x16x32_bf16 v[222:225], v[186:189], v[34:37], v[222:225]
	v_mfma_f32_16x16x32_bf16 v[130:133], v[186:189], v[58:61], v[130:133]
	s_waitcnt lgkmcnt(5)
	v_mfma_f32_16x16x32_bf16 v[186:189], v[206:209], v[46:49], v[222:225]
	v_mfma_f32_16x16x32_bf16 v[130:133], v[206:209], v[54:57], v[130:133]
	s_waitcnt lgkmcnt(4)
	v_mfma_f32_16x16x32_bf16 v[186:189], v[210:213], v[42:45], v[186:189]
	v_mfma_f32_16x16x32_bf16 v[206:209], v[210:213], v[50:53], v[130:133]
	s_waitcnt lgkmcnt(3)
	v_mfma_f32_16x16x32_bf16 v[130:133], v[198:201], v[38:41], 0
	v_mfma_f32_16x16x32_bf16 v[198:201], v[198:201], v[62:65], 0
	s_waitcnt lgkmcnt(2)
	v_mfma_f32_16x16x32_bf16 v[130:133], v[202:205], v[34:37], v[130:133]
	v_mfma_f32_16x16x32_bf16 v[198:201], v[202:205], v[58:61], v[198:201]
	s_waitcnt lgkmcnt(1)
	v_mfma_f32_16x16x32_bf16 v[130:133], v[214:217], v[46:49], v[130:133]
	v_mfma_f32_16x16x32_bf16 v[198:201], v[214:217], v[54:57], v[198:201]
	s_waitcnt lgkmcnt(0)
	v_mfma_f32_16x16x32_bf16 v[130:133], v[218:221], v[42:45], v[130:133]
	v_mfma_f32_16x16x32_bf16 v[198:201], v[218:221], v[50:53], v[198:201]
	v_add_u32_e32 v247, 0xd800, v149
	v_add_u32_e32 v248, 0xe000, v149
	v_add_u32_e32 v249, 0xe800, v149
	s_nop 0
	ds_read2_b64 v[230:233], v172 offset1:4
	ds_read2_b64 v[234:237], v247 offset0:32 offset1:36
	ds_read2_b64 v[238:241], v248 offset0:64 offset1:68
	ds_read2_b64 v[242:245], v249 offset0:96 offset1:100
	v_fma_f32 v0, v178, s53, -v170
	v_exp_f32_e32 v202, v0
	v_fma_f32 v0, v179, s53, -v170
	v_exp_f32_e32 v204, v0
	v_fma_f32 v0, v180, s53, -v170
	v_exp_f32_e32 v210, v0
	v_fma_f32 v0, v181, s53, -v170
	v_exp_f32_e32 v212, v0
	v_fma_f32 v0, v194, s53, -v170
	v_exp_f32_e32 v194, v0
	v_fma_f32 v0, v195, s53, -v170
	v_exp_f32_e32 v214, v0
	v_fma_f32 v0, v196, s53, -v170
	v_exp_f32_e32 v196, v0
	v_fma_f32 v0, v197, s53, -v170
	v_exp_f32_e32 v216, v0
	v_fma_f32 v0, v186, s53, -v170
	v_exp_f32_e32 v186, v0
	v_fma_f32 v0, v187, s53, -v170
	v_exp_f32_e32 v218, v0
	v_fma_f32 v0, v188, s53, -v170
	v_exp_f32_e32 v188, v0
	v_fma_f32 v0, v189, s53, -v170
	v_exp_f32_e32 v220, v0
	v_fma_f32 v0, v130, s53, -v170
	v_exp_f32_e32 v222, v0
	v_fma_f32 v0, v131, s53, -v170
	v_exp_f32_e32 v224, v0
	v_fma_f32 v0, v132, s53, -v170
	v_exp_f32_e32 v226, v0
	v_fma_f32 v0, v133, s53, -v170
	v_exp_f32_e32 v228, v0
	v_fma_f32 v0, v182, s53, -v170
	v_exp_f32_e32 v203, v0
	v_fma_f32 v0, v183, s53, -v170
	v_exp_f32_e32 v205, v0
	v_fma_f32 v0, v184, s53, -v170
	v_exp_f32_e32 v211, v0
	v_fma_f32 v0, v185, s53, -v170
	v_exp_f32_e32 v213, v0
	v_fma_f32 v0, v190, s53, -v170
	v_exp_f32_e32 v195, v0
	v_fma_f32 v0, v191, s53, -v170
	v_pk_add_f32 v[182:183], v[202:203], 0 op_sel_hi:[1,0]
	v_exp_f32_e32 v215, v0
	v_fma_f32 v0, v192, s53, -v170
	v_pk_add_f32 v[182:183], v[204:205], v[182:183]
	v_exp_f32_e32 v197, v0
	v_fma_f32 v0, v193, s53, -v170
	v_pk_add_f32 v[182:183], v[210:211], v[182:183]
	v_exp_f32_e32 v217, v0
	v_pk_add_f32 v[182:183], v[212:213], v[182:183]
	v_fma_f32 v0, v206, s53, -v170
; __device__ __forceinline__ f32x4 mfma16(bf16x8 a, bf16x8 b, f32x4 c) { return __builtin_amdgcn_mfma_f32_16x16x32_bf16(a, b, c, 0, 0, 0); }
; #define SCHED() __builtin_amdgcn_sched_barrier(0)
; __device__ __forceinline__ void attn_item(const bf16_t* __restrict__ Q, const bf16_t* __restrict__ Kp, const bf16_t* __restrict__ VT,
;                                           bf16_t* __restrict__ O, int ldo, int nvalid, const float* __restrict__ qn, const float* __restrict__ kn, bf16_t* sm) {
;     ...
;       bf16x8 pf[2][2];
; #pragma unroll
;       for (int g = 0; g < 2; ++g) {
;         float rs = 0.f;
; #pragma unroll
;         for (int kt = 0; kt < 4; ++kt)
; #pragma unroll
;           for (int j = 0; j < 4; ++j) {
;             float pv = __builtin_amdgcn_exp2f(s[g][kt][j] * cscale - mc);
;             s[g][kt][j] = pv;
;             rs += pv;
;           }
;         l[g] += rs;
; #pragma unroll
;         for (int u = 0; u < 2; ++u) {
;           u32x4 w = {pack2(s[g][2 * u][0], s[g][2 * u][1]), pack2(s[g][2 * u][2], s[g][2 * u][3]),
;                      pack2(s[g][2 * u + 1][0], s[g][2 * u + 1][1]), pack2(s[g][2 * u + 1][2], s[g][2 * u + 1][3])};
;           pf[g][u] = *reinterpret_cast<bf16x8*>(&w);
;         }
;       }
; #pragma unroll
;       for (int u = 0; u < 2; ++u) {
;         bf16x8 vf[8];
; #pragma unroll
;         for (int dt = 0; dt < 8; ++dt) {
;           u32x2 v0 = *(const u32x2*)(sV + (dt * 16 + l15) * 72 + (2 * u) * 16 + quad * 4);
;           u32x2 v1 = *(const u32x2*)(sV + (dt * 16 + l15) * 72 + (2 * u + 1) * 16 + quad * 4);
;           u32x4 w = {v0.x, v0.y, v1.x, v1.y};
;           vf[dt] = *reinterpret_cast<bf16x8*>(&w);
;         }
;         SCHED();
; #pragma unroll
;         for (int dt = 0; dt < 8; ++dt) {
;           o[0][dt] = mfma16(vf[dt], pf[0][u], o[0][dt]);
;           o[1][dt] = mfma16(vf[dt], pf[1][u], o[1][dt]);
;         }
;         SCHED();
;       }
	v_pk_add_f32 v[182:183], v[182:183], v[194:195]
	v_exp_f32_e32 v187, v0
	v_fma_f32 v0, v207, s53, -v170
	v_pk_add_f32 v[182:183], v[214:215], v[182:183]
	v_exp_f32_e32 v219, v0
	v_fma_f32 v0, v208, s53, -v170
	v_pk_add_f32 v[182:183], v[196:197], v[182:183]
	v_exp_f32_e32 v189, v0
	v_fma_f32 v0, v209, s53, -v170
	v_pk_add_f32 v[182:183], v[216:217], v[182:183]
	v_exp_f32_e32 v221, v0
	v_fma_f32 v0, v198, s53, -v170
	v_exp_f32_e32 v223, v0
	v_fma_f32 v0, v199, s53, -v170
	v_pk_add_f32 v[182:183], v[182:183], v[186:187]
	v_exp_f32_e32 v225, v0
	v_fma_f32 v0, v200, s53, -v170
	v_pk_add_f32 v[182:183], v[218:219], v[182:183]
	v_exp_f32_e32 v227, v0
	v_fma_f32 v0, v201, s53, -v170
	v_pk_add_f32 v[182:183], v[188:189], v[182:183]
	v_exp_f32_e32 v229, v0
	v_pk_add_f32 v[182:183], v[220:221], v[182:183]
	v_cvt_pk_bf16_f32 v178, v202, v204
	v_cvt_pk_bf16_f32 v179, v210, v212
	v_cvt_pk_bf16_f32 v180, v194, v214
	v_cvt_pk_bf16_f32 v181, v196, v216
	v_cvt_pk_bf16_f32 v130, v186, v218
	s_nop 0
	v_pk_add_f32 v[182:183], v[182:183], v[222:223]
	v_cvt_pk_bf16_f32 v131, v188, v220
	v_cvt_pk_bf16_f32 v132, v222, v224
	v_cvt_pk_bf16_f32 v133, v226, v228
	v_add_u32_e32 v0, 0xd800, v149
	v_pk_add_f32 v[182:183], v[224:225], v[182:183]
	v_add_u32_e32 v222, 0xe000, v149
	v_pk_add_f32 v[182:183], v[226:227], v[182:183]
	v_add_u32_e32 v224, 0xf000, v149
	v_pk_add_f32 v[182:183], v[228:229], v[182:183]
	s_nop 0
	v_pk_add_f32 v[144:145], v[144:145], v[182:183]
	v_cvt_pk_bf16_f32 v182, v203, v205
	v_cvt_pk_bf16_f32 v183, v211, v213
	v_cvt_pk_bf16_f32 v184, v195, v215
	v_cvt_pk_bf16_f32 v185, v197, v217
	v_cvt_pk_bf16_f32 v186, v187, v219
	v_cvt_pk_bf16_f32 v187, v189, v221
	v_cvt_pk_bf16_f32 v188, v223, v225
	v_add_u32_e32 v223, 0xe800, v149
	v_add_u32_e32 v225, 0xf800, v149
	v_cvt_pk_bf16_f32 v189, v227, v229
	ds_read2_b64 v[206:209], v224 offset0:128 offset1:132
	ds_read2_b64 v[210:213], v225 offset0:160 offset1:164
	ds_read_b64 v[214:215], v172 offset:13824
	ds_read_b64 v[216:217], v173 offset:32
	ds_read_b64 v[218:219], v172 offset:16128
	ds_read_b64 v[220:221], v174 offset:32
	s_waitcnt lgkmcnt(9)
	v_mfma_f32_16x16x32_bf16 v[94:97], v[230:233], v[178:181], v[94:97]
	v_mfma_f32_16x16x32_bf16 v[30:33], v[230:233], v[182:185], v[30:33]
	s_waitcnt lgkmcnt(8)
	v_mfma_f32_16x16x32_bf16 v[90:93], v[234:237], v[178:181], v[90:93]
	v_mfma_f32_16x16x32_bf16 v[26:29], v[234:237], v[182:185], v[26:29]
	s_waitcnt lgkmcnt(7)
	v_mfma_f32_16x16x32_bf16 v[86:89], v[238:241], v[178:181], v[86:89]
	v_mfma_f32_16x16x32_bf16 v[22:25], v[238:241], v[182:185], v[22:25]
	s_waitcnt lgkmcnt(6)
	v_mfma_f32_16x16x32_bf16 v[82:85], v[242:245], v[178:181], v[82:85]
	v_mfma_f32_16x16x32_bf16 v[18:21], v[242:245], v[182:185], v[18:21]
	s_waitcnt lgkmcnt(5)
	v_mfma_f32_16x16x32_bf16 v[78:81], v[206:209], v[178:181], v[78:81]
	v_mfma_f32_16x16x32_bf16 v[14:17], v[206:209], v[182:185], v[14:17]
	s_waitcnt lgkmcnt(4)
	v_mfma_f32_16x16x32_bf16 v[74:77], v[210:213], v[178:181], v[74:77]
	v_mfma_f32_16x16x32_bf16 v[10:13], v[210:213], v[182:185], v[10:13]
	s_waitcnt lgkmcnt(2)
	v_mfma_f32_16x16x32_bf16 v[70:73], v[214:217], v[178:181], v[70:73]
	v_mfma_f32_16x16x32_bf16 v[6:9], v[214:217], v[182:185], v[6:9]
	s_waitcnt lgkmcnt(0)
	v_mfma_f32_16x16x32_bf16 v[66:69], v[218:221], v[178:181], v[66:69]
	v_mfma_f32_16x16x32_bf16 v[2:5], v[218:221], v[182:185], v[2:5]
	ds_read2_b64 v[178:181], v172 offset0:8 offset1:12
	ds_read2_b64 v[182:185], v0 offset0:40 offset1:44
	ds_read2_b64 v[190:193], v222 offset0:72 offset1:76
	ds_read2_b64 v[194:197], v223 offset0:104 offset1:108
	ds_read2_b64 v[198:201], v224 offset0:136 offset1:140
	ds_read2_b64 v[202:205], v225 offset0:168 offset1:172
	ds_read_b64 v[206:207], v175 offset:13824
	ds_read_b64 v[208:209], v176 offset:32
	ds_read_b64 v[212:213], v177 offset:32
	ds_read_b64 v[210:211], v175 offset:16128
	s_waitcnt lgkmcnt(9)
	v_mfma_f32_16x16x32_bf16 v[94:97], v[178:181], v[130:133], v[94:97]
	v_mfma_f32_16x16x32_bf16 v[30:33], v[178:181], v[186:189], v[30:33]
	s_waitcnt lgkmcnt(8)
	v_mfma_f32_16x16x32_bf16 v[90:93], v[182:185], v[130:133], v[90:93]
	v_mfma_f32_16x16x32_bf16 v[26:29], v[182:185], v[186:189], v[26:29]
	s_waitcnt lgkmcnt(7)
	v_mfma_f32_16x16x32_bf16 v[86:89], v[190:193], v[130:133], v[86:89]
	v_mfma_f32_16x16x32_bf16 v[22:25], v[190:193], v[186:189], v[22:25]
	s_waitcnt lgkmcnt(6)
	v_mfma_f32_16x16x32_bf16 v[82:85], v[194:197], v[130:133], v[82:85]
	v_mfma_f32_16x16x32_bf16 v[18:21], v[194:197], v[186:189], v[18:21]
	s_waitcnt lgkmcnt(5)
	v_mfma_f32_16x16x32_bf16 v[78:81], v[198:201], v[130:133], v[78:81]
	v_mfma_f32_16x16x32_bf16 v[14:17], v[198:201], v[186:189], v[14:17]
	s_waitcnt lgkmcnt(4)
	v_mfma_f32_16x16x32_bf16 v[74:77], v[202:205], v[130:133], v[74:77]
	v_mfma_f32_16x16x32_bf16 v[10:13], v[202:205], v[186:189], v[10:13]
	s_waitcnt lgkmcnt(2)
	v_mfma_f32_16x16x32_bf16 v[70:73], v[206:209], v[130:133], v[70:73]
	v_mfma_f32_16x16x32_bf16 v[6:9], v[206:209], v[186:189], v[6:9]
	s_waitcnt lgkmcnt(0)
	v_mfma_f32_16x16x32_bf16 v[66:69], v[210:213], v[130:133], v[66:69]
	v_mfma_f32_16x16x32_bf16 v[2:5], v[210:213], v[186:189], v[2:5]
	s_branch .LBB0_645
